# v15
# speedup vs baseline: 1.0528x; 1.0018x over previous
; #define SBAR() __builtin_amdgcn_sched_barrier(0)
; DEVINL void phase_merge(const Params& p, int l, char* shm) {
;     ...
;       const int hoff = br < 2 ? 2048 : 0; const bool notlast = br < 2;
; #pragma unroll
;       for (int ai = 0; ai < 2; ++ai)
; #pragma unroll
;         for (int m = 0; m < 4; ++m) {
;           const u16* grow = MGT + (size_t)(brow + ai * 128 + wr * 64 + m * 16 + fr) * 6144 + br * 2048 + bcol + wc * 32 + fq * 4;
; #pragma unroll
;           for (int bj = 0; bj < 2; ++bj)
; #pragma unroll
;             for (int n = 0; n < 2; ++n) {
;               const u32x2 g = *reinterpret_cast<const u32x2*>(grow + bj * 128 + n * 16);
;               const u32x2 h = *reinterpret_cast<const u32x2*>(grow + hoff + bj * 128 + n * 16);
;               const float r0 = notlast ? __builtin_amdgcn_rcpf(fmaxf(__uint_as_float(h[0] << 16), 1e-18f)) : 1.f;
;               const float r1 = notlast ? __builtin_amdgcn_rcpf(fmaxf(__uint_as_float(h[0] & 0xffff0000u), 1e-18f)) : 1.f;
;               const float r2 = notlast ? __builtin_amdgcn_rcpf(fmaxf(__uint_as_float(h[1] << 16), 1e-18f)) : 1.f;
;               const float r3 = notlast ? __builtin_amdgcn_rcpf(fmaxf(__uint_as_float(h[1] & 0xffff0000u), 1e-18f)) : 1.f;
;               acc[ai][bj][m][n][0] *= __uint_as_float(g[0] << 16) * r0; acc[ai][bj][m][n][1] *= __uint_as_float(g[0] & 0xffff0000u) * r1;
;               acc[ai][bj][m][n][2] *= __uint_as_float(g[1] << 16) * r2; acc[ai][bj][m][n][3] *= __uint_as_float(g[1] & 0xffff0000u) * r3;
;             }
;           SBAR();
;         }
.LBB0_671:
	s_or_b64 exec, exec, s[28:29]
	s_cmp_eq_u32 s27, 2
	s_cselect_b64 s[28:29], -1, 0
	s_and_b64 vcc, s[28:29], exec
	v_mov_b32_e32 v112, v186
	s_cselect_b32 s34, 0, 0x1000
	s_lshl_b32 s75, s27, 12
	s_add_u32 vcc_lo, s24, s75
	v_ashrrev_i32_e32 v114, 2, v112
	v_and_b32_e32 v114, 0xffffffc0, v114
	v_and_or_b32 v115, v112, 15, s41
	s_addc_u32 vcc_hi, s26, 0
	v_lshrrev_b32_e32 v132, 1, v112
	v_and_b32_e32 v112, 0xc0, v112
	v_add_u32_e32 v136, v115, v114
	v_lshl_add_u64 v[114:115], vcc, 0, v[112:113]
	v_and_b32_e32 v112, 24, v132
	v_lshl_add_u64 v[114:115], v[114:115], 0, v[112:113]
	v_mad_i64_i32 v[132:133], vcc, v136, s33, v[114:115]
	v_lshl_add_u64 v[134:135], v[132:133], 0, s[34:35]
	global_load_dwordx2 v[204:205], v[132:133], off
	global_load_dwordx2 v[206:207], v[134:135], off
	global_load_dwordx2 v[208:209], v[132:133], off offset:32
	global_load_dwordx2 v[210:211], v[134:135], off offset:32
	global_load_dwordx2 v[212:213], v[132:133], off offset:256
	global_load_dwordx2 v[214:215], v[134:135], off offset:256
	global_load_dwordx2 v[216:217], v[132:133], off offset:288
	global_load_dwordx2 v[218:219], v[134:135], off offset:288
	v_or_b32_e32 v112, 16, v136
	v_mad_i64_i32 v[132:133], vcc, v112, s33, v[114:115]
	v_lshl_add_u64 v[134:135], v[132:133], 0, s[34:35]
	global_load_dwordx2 v[220:221], v[132:133], off
	global_load_dwordx2 v[222:223], v[134:135], off
	global_load_dwordx2 v[224:225], v[132:133], off offset:32
	global_load_dwordx2 v[226:227], v[134:135], off offset:32
	global_load_dwordx2 v[228:229], v[132:133], off offset:256
	global_load_dwordx2 v[230:231], v[134:135], off offset:256
	global_load_dwordx2 v[232:233], v[132:133], off offset:288
	global_load_dwordx2 v[234:235], v[134:135], off offset:288
	s_waitcnt vmcnt(14)
	v_lshlrev_b32_e32 v142, 16, v204
	v_lshlrev_b32_e32 v112, 16, v206
	v_max_f32_e32 v112, v112, v112
	v_max_f32_e32 v112, 0x219392ef, v112
	v_and_b32_e32 v137, 0xffff0000, v206
	v_rcp_f32_e32 v112, v112
	v_max_f32_e32 v137, v137, v137
	v_max_f32_e32 v137, 0x219392ef, v137
	v_lshlrev_b32_e32 v206, 16, v207
	v_rcp_f32_e32 v137, v137
	v_max_f32_e32 v206, v206, v206
	v_max_f32_e32 v206, 0x219392ef, v206
	v_and_b32_e32 v207, 0xffff0000, v207
	v_cndmask_b32_e64 v112, v112, 1.0, s[28:29]
	v_rcp_f32_e32 v206, v206
	v_max_f32_e32 v207, v207, v207
	v_max_f32_e32 v207, 0x219392ef, v207
	v_mul_f32_e32 v112, v112, v142
	v_cndmask_b32_e64 v137, v137, 1.0, s[28:29]
	v_rcp_f32_e32 v207, v207
	v_mul_f32_e32 v0, v0, v112
	v_and_b32_e32 v112, 0xffff0000, v204
	v_mul_f32_e32 v112, v137, v112
	v_cndmask_b32_e64 v206, v206, 1.0, s[28:29]
	v_mul_f32_e32 v1, v1, v112
	v_lshlrev_b32_e32 v112, 16, v205
	v_mul_f32_e32 v112, v206, v112
	v_cndmask_b32_e64 v207, v207, 1.0, s[28:29]
	v_mul_f32_e32 v2, v2, v112
	v_and_b32_e32 v112, 0xffff0000, v205
	v_mul_f32_e32 v112, v207, v112
	v_mul_f32_e32 v3, v3, v112
	s_waitcnt vmcnt(12)
	v_lshlrev_b32_e32 v142, 16, v208
	v_lshlrev_b32_e32 v112, 16, v210
	v_max_f32_e32 v112, v112, v112
	v_max_f32_e32 v112, 0x219392ef, v112
	v_and_b32_e32 v137, 0xffff0000, v210
	v_rcp_f32_e32 v112, v112
	v_max_f32_e32 v137, v137, v137
	v_max_f32_e32 v137, 0x219392ef, v137
	v_lshlrev_b32_e32 v210, 16, v211
	v_rcp_f32_e32 v137, v137
	v_max_f32_e32 v210, v210, v210
	v_max_f32_e32 v210, 0x219392ef, v210
	v_and_b32_e32 v211, 0xffff0000, v211
	v_cndmask_b32_e64 v112, v112, 1.0, s[28:29]
	v_rcp_f32_e32 v210, v210
	v_max_f32_e32 v211, v211, v211
	v_max_f32_e32 v211, 0x219392ef, v211
	v_mul_f32_e32 v112, v112, v142
	v_cndmask_b32_e64 v137, v137, 1.0, s[28:29]
	v_rcp_f32_e32 v211, v211
	v_mul_f32_e32 v4, v4, v112
	v_and_b32_e32 v112, 0xffff0000, v208
	v_mul_f32_e32 v112, v137, v112
	v_cndmask_b32_e64 v210, v210, 1.0, s[28:29]
	v_mul_f32_e32 v5, v5, v112
	v_lshlrev_b32_e32 v112, 16, v209
	v_mul_f32_e32 v112, v210, v112
	v_cndmask_b32_e64 v211, v211, 1.0, s[28:29]
	v_mul_f32_e32 v6, v6, v112
	v_and_b32_e32 v112, 0xffff0000, v209
	v_mul_f32_e32 v112, v211, v112
	v_mul_f32_e32 v7, v7, v112
	s_waitcnt vmcnt(10)
	v_lshlrev_b32_e32 v142, 16, v212
	v_lshlrev_b32_e32 v112, 16, v214
	v_max_f32_e32 v112, v112, v112
	v_max_f32_e32 v112, 0x219392ef, v112
	v_and_b32_e32 v137, 0xffff0000, v214
	v_rcp_f32_e32 v112, v112
	v_max_f32_e32 v137, v137, v137
	v_max_f32_e32 v137, 0x219392ef, v137
	v_lshlrev_b32_e32 v214, 16, v215
	v_rcp_f32_e32 v137, v137
	v_max_f32_e32 v214, v214, v214
	v_max_f32_e32 v214, 0x219392ef, v214
	v_and_b32_e32 v215, 0xffff0000, v215
	v_cndmask_b32_e64 v112, v112, 1.0, s[28:29]
	v_rcp_f32_e32 v214, v214
	v_max_f32_e32 v215, v215, v215
	v_max_f32_e32 v215, 0x219392ef, v215
	v_mul_f32_e32 v112, v112, v142
	v_cndmask_b32_e64 v137, v137, 1.0, s[28:29]
	v_rcp_f32_e32 v215, v215
	v_mul_f32_e32 v8, v8, v112
	v_and_b32_e32 v112, 0xffff0000, v212
	v_mul_f32_e32 v112, v137, v112
	v_cndmask_b32_e64 v214, v214, 1.0, s[28:29]
	v_mul_f32_e32 v9, v9, v112
	v_lshlrev_b32_e32 v112, 16, v213
	v_mul_f32_e32 v112, v214, v112
	v_cndmask_b32_e64 v215, v215, 1.0, s[28:29]
	v_mul_f32_e32 v10, v10, v112
	v_and_b32_e32 v112, 0xffff0000, v213
	v_mul_f32_e32 v112, v215, v112
	v_mul_f32_e32 v11, v11, v112
	s_waitcnt vmcnt(8)
; #define SBAR() __builtin_amdgcn_sched_barrier(0)
; DEVINL void phase_merge(const Params& p, int l, char* shm) {
;     ...
;       const int hoff = br < 2 ? 2048 : 0; const bool notlast = br < 2;
; #pragma unroll
;       for (int ai = 0; ai < 2; ++ai)
; #pragma unroll
;         for (int m = 0; m < 4; ++m) {
;           const u16* grow = MGT + (size_t)(brow + ai * 128 + wr * 64 + m * 16 + fr) * 6144 + br * 2048 + bcol + wc * 32 + fq * 4;
; #pragma unroll
;           for (int bj = 0; bj < 2; ++bj)
; #pragma unroll
;             for (int n = 0; n < 2; ++n) {
;               const u32x2 g = *reinterpret_cast<const u32x2*>(grow + bj * 128 + n * 16);
;               const u32x2 h = *reinterpret_cast<const u32x2*>(grow + hoff + bj * 128 + n * 16);
;               const float r0 = notlast ? __builtin_amdgcn_rcpf(fmaxf(__uint_as_float(h[0] << 16), 1e-18f)) : 1.f;
;               const float r1 = notlast ? __builtin_amdgcn_rcpf(fmaxf(__uint_as_float(h[0] & 0xffff0000u), 1e-18f)) : 1.f;
;               const float r2 = notlast ? __builtin_amdgcn_rcpf(fmaxf(__uint_as_float(h[1] << 16), 1e-18f)) : 1.f;
;               const float r3 = notlast ? __builtin_amdgcn_rcpf(fmaxf(__uint_as_float(h[1] & 0xffff0000u), 1e-18f)) : 1.f;
;               acc[ai][bj][m][n][0] *= __uint_as_float(g[0] << 16) * r0; acc[ai][bj][m][n][1] *= __uint_as_float(g[0] & 0xffff0000u) * r1;
;               acc[ai][bj][m][n][2] *= __uint_as_float(g[1] << 16) * r2; acc[ai][bj][m][n][3] *= __uint_as_float(g[1] & 0xffff0000u) * r3;
;             }
;           SBAR();
;         }
	v_lshlrev_b32_e32 v142, 16, v216
	v_lshlrev_b32_e32 v112, 16, v218
	v_max_f32_e32 v112, v112, v112
	v_max_f32_e32 v112, 0x219392ef, v112
	v_and_b32_e32 v137, 0xffff0000, v218
	v_rcp_f32_e32 v112, v112
	v_max_f32_e32 v137, v137, v137
	v_max_f32_e32 v137, 0x219392ef, v137
	v_lshlrev_b32_e32 v218, 16, v219
	v_rcp_f32_e32 v137, v137
	v_max_f32_e32 v218, v218, v218
	v_max_f32_e32 v218, 0x219392ef, v218
	v_and_b32_e32 v219, 0xffff0000, v219
	v_cndmask_b32_e64 v112, v112, 1.0, s[28:29]
	v_rcp_f32_e32 v218, v218
	v_max_f32_e32 v219, v219, v219
	v_max_f32_e32 v219, 0x219392ef, v219
	v_mul_f32_e32 v112, v112, v142
	v_cndmask_b32_e64 v137, v137, 1.0, s[28:29]
	v_rcp_f32_e32 v219, v219
	v_mul_f32_e32 v16, v16, v112
	v_and_b32_e32 v112, 0xffff0000, v216
	v_mul_f32_e32 v112, v137, v112
	v_cndmask_b32_e64 v218, v218, 1.0, s[28:29]
	v_mul_f32_e32 v17, v17, v112
	v_lshlrev_b32_e32 v112, 16, v217
	v_mul_f32_e32 v112, v218, v112
	v_cndmask_b32_e64 v219, v219, 1.0, s[28:29]
	v_mul_f32_e32 v18, v18, v112
	v_and_b32_e32 v112, 0xffff0000, v217
	v_mul_f32_e32 v112, v219, v112
	v_mul_f32_e32 v19, v19, v112
	v_or_b32_e32 v112, 32, v136
	v_mad_i64_i32 v[132:133], vcc, v112, s33, v[114:115]
	v_lshl_add_u64 v[134:135], v[132:133], 0, s[34:35]
	global_load_dwordx2 v[204:205], v[132:133], off
	global_load_dwordx2 v[206:207], v[134:135], off
	global_load_dwordx2 v[208:209], v[132:133], off offset:32
	global_load_dwordx2 v[210:211], v[134:135], off offset:32
	global_load_dwordx2 v[212:213], v[132:133], off offset:256
	global_load_dwordx2 v[214:215], v[134:135], off offset:256
	global_load_dwordx2 v[216:217], v[132:133], off offset:288
	global_load_dwordx2 v[218:219], v[134:135], off offset:288
	s_waitcnt vmcnt(14)
	v_lshlrev_b32_e32 v142, 16, v220
	v_lshlrev_b32_e32 v112, 16, v222
	v_max_f32_e32 v112, v112, v112
	v_max_f32_e32 v112, 0x219392ef, v112
	v_and_b32_e32 v137, 0xffff0000, v222
	v_rcp_f32_e32 v112, v112
	v_max_f32_e32 v137, v137, v137
	v_max_f32_e32 v137, 0x219392ef, v137
	v_lshlrev_b32_e32 v222, 16, v223
	v_rcp_f32_e32 v137, v137
	v_max_f32_e32 v222, v222, v222
	v_max_f32_e32 v222, 0x219392ef, v222
	v_and_b32_e32 v223, 0xffff0000, v223
	v_cndmask_b32_e64 v112, v112, 1.0, s[28:29]
	v_rcp_f32_e32 v222, v222
	v_max_f32_e32 v223, v223, v223
	v_max_f32_e32 v223, 0x219392ef, v223
	v_mul_f32_e32 v112, v112, v142
	v_cndmask_b32_e64 v137, v137, 1.0, s[28:29]
	v_rcp_f32_e32 v223, v223
	v_mul_f32_e32 v20, v20, v112
	v_and_b32_e32 v112, 0xffff0000, v220
	v_mul_f32_e32 v112, v137, v112
	v_cndmask_b32_e64 v222, v222, 1.0, s[28:29]
	v_mul_f32_e32 v21, v21, v112
	v_lshlrev_b32_e32 v112, 16, v221
	v_mul_f32_e32 v112, v222, v112
	v_cndmask_b32_e64 v223, v223, 1.0, s[28:29]
	v_mul_f32_e32 v22, v22, v112
	v_and_b32_e32 v112, 0xffff0000, v221
	v_mul_f32_e32 v112, v223, v112
	v_mul_f32_e32 v23, v23, v112
	s_waitcnt vmcnt(12)
	v_lshlrev_b32_e32 v142, 16, v224
	v_lshlrev_b32_e32 v112, 16, v226
	v_max_f32_e32 v112, v112, v112
	v_max_f32_e32 v112, 0x219392ef, v112
	v_and_b32_e32 v137, 0xffff0000, v226
	v_rcp_f32_e32 v112, v112
	v_max_f32_e32 v137, v137, v137
	v_max_f32_e32 v137, 0x219392ef, v137
	v_lshlrev_b32_e32 v226, 16, v227
	v_rcp_f32_e32 v137, v137
	v_max_f32_e32 v226, v226, v226
	v_max_f32_e32 v226, 0x219392ef, v226
	v_and_b32_e32 v227, 0xffff0000, v227
	v_cndmask_b32_e64 v112, v112, 1.0, s[28:29]
	v_rcp_f32_e32 v226, v226
	v_max_f32_e32 v227, v227, v227
	v_max_f32_e32 v227, 0x219392ef, v227
	v_mul_f32_e32 v112, v112, v142
	v_cndmask_b32_e64 v137, v137, 1.0, s[28:29]
	v_rcp_f32_e32 v227, v227
	v_mul_f32_e32 v24, v24, v112
	v_and_b32_e32 v112, 0xffff0000, v224
	v_mul_f32_e32 v112, v137, v112
	v_cndmask_b32_e64 v226, v226, 1.0, s[28:29]
	v_mul_f32_e32 v25, v25, v112
	v_lshlrev_b32_e32 v112, 16, v225
	v_mul_f32_e32 v112, v226, v112
	v_cndmask_b32_e64 v227, v227, 1.0, s[28:29]
	v_mul_f32_e32 v26, v26, v112
	v_and_b32_e32 v112, 0xffff0000, v225
	v_mul_f32_e32 v112, v227, v112
	v_mul_f32_e32 v27, v27, v112
	s_waitcnt vmcnt(10)
	v_lshlrev_b32_e32 v142, 16, v228
	v_lshlrev_b32_e32 v112, 16, v230
	v_max_f32_e32 v112, v112, v112
	v_max_f32_e32 v112, 0x219392ef, v112
	v_and_b32_e32 v137, 0xffff0000, v230
	v_rcp_f32_e32 v112, v112
	v_max_f32_e32 v137, v137, v137
	v_max_f32_e32 v137, 0x219392ef, v137
	v_lshlrev_b32_e32 v230, 16, v231
	v_rcp_f32_e32 v137, v137
	v_max_f32_e32 v230, v230, v230
	v_max_f32_e32 v230, 0x219392ef, v230
	v_and_b32_e32 v231, 0xffff0000, v231
	v_cndmask_b32_e64 v112, v112, 1.0, s[28:29]
	v_rcp_f32_e32 v230, v230
	v_max_f32_e32 v231, v231, v231
	v_max_f32_e32 v231, 0x219392ef, v231
	v_mul_f32_e32 v112, v112, v142
	v_cndmask_b32_e64 v137, v137, 1.0, s[28:29]
	v_rcp_f32_e32 v231, v231
	v_mul_f32_e32 v32, v32, v112
	v_and_b32_e32 v112, 0xffff0000, v228
	v_mul_f32_e32 v112, v137, v112
	v_cndmask_b32_e64 v230, v230, 1.0, s[28:29]
	v_mul_f32_e32 v33, v33, v112
	v_lshlrev_b32_e32 v112, 16, v229
	v_mul_f32_e32 v112, v230, v112
	v_cndmask_b32_e64 v231, v231, 1.0, s[28:29]
	v_mul_f32_e32 v34, v34, v112
	v_and_b32_e32 v112, 0xffff0000, v229
	v_mul_f32_e32 v112, v231, v112
	v_mul_f32_e32 v35, v35, v112
	s_waitcnt vmcnt(8)
; #define SBAR() __builtin_amdgcn_sched_barrier(0)
; DEVINL void phase_merge(const Params& p, int l, char* shm) {
;     ...
;       const int hoff = br < 2 ? 2048 : 0; const bool notlast = br < 2;
; #pragma unroll
;       for (int ai = 0; ai < 2; ++ai)
; #pragma unroll
;         for (int m = 0; m < 4; ++m) {
;           const u16* grow = MGT + (size_t)(brow + ai * 128 + wr * 64 + m * 16 + fr) * 6144 + br * 2048 + bcol + wc * 32 + fq * 4;
; #pragma unroll
;           for (int bj = 0; bj < 2; ++bj)
; #pragma unroll
;             for (int n = 0; n < 2; ++n) {
;               const u32x2 g = *reinterpret_cast<const u32x2*>(grow + bj * 128 + n * 16);
;               const u32x2 h = *reinterpret_cast<const u32x2*>(grow + hoff + bj * 128 + n * 16);
;               const float r0 = notlast ? __builtin_amdgcn_rcpf(fmaxf(__uint_as_float(h[0] << 16), 1e-18f)) : 1.f;
;               const float r1 = notlast ? __builtin_amdgcn_rcpf(fmaxf(__uint_as_float(h[0] & 0xffff0000u), 1e-18f)) : 1.f;
;               const float r2 = notlast ? __builtin_amdgcn_rcpf(fmaxf(__uint_as_float(h[1] << 16), 1e-18f)) : 1.f;
;               const float r3 = notlast ? __builtin_amdgcn_rcpf(fmaxf(__uint_as_float(h[1] & 0xffff0000u), 1e-18f)) : 1.f;
;               acc[ai][bj][m][n][0] *= __uint_as_float(g[0] << 16) * r0; acc[ai][bj][m][n][1] *= __uint_as_float(g[0] & 0xffff0000u) * r1;
;               acc[ai][bj][m][n][2] *= __uint_as_float(g[1] << 16) * r2; acc[ai][bj][m][n][3] *= __uint_as_float(g[1] & 0xffff0000u) * r3;
;             }
;           SBAR();
;         }
	v_lshlrev_b32_e32 v142, 16, v232
	v_lshlrev_b32_e32 v112, 16, v234
	v_max_f32_e32 v112, v112, v112
	v_max_f32_e32 v112, 0x219392ef, v112
	v_and_b32_e32 v137, 0xffff0000, v234
	v_rcp_f32_e32 v112, v112
	v_max_f32_e32 v137, v137, v137
	v_max_f32_e32 v137, 0x219392ef, v137
	v_lshlrev_b32_e32 v234, 16, v235
	v_rcp_f32_e32 v137, v137
	v_max_f32_e32 v234, v234, v234
	v_max_f32_e32 v234, 0x219392ef, v234
	v_and_b32_e32 v235, 0xffff0000, v235
	v_cndmask_b32_e64 v112, v112, 1.0, s[28:29]
	v_rcp_f32_e32 v234, v234
	v_max_f32_e32 v235, v235, v235
	v_max_f32_e32 v235, 0x219392ef, v235
	v_mul_f32_e32 v112, v112, v142
	v_cndmask_b32_e64 v137, v137, 1.0, s[28:29]
	v_rcp_f32_e32 v235, v235
	v_mul_f32_e32 v48, v48, v112
	v_and_b32_e32 v112, 0xffff0000, v232
	v_mul_f32_e32 v112, v137, v112
	v_cndmask_b32_e64 v234, v234, 1.0, s[28:29]
	v_mul_f32_e32 v49, v49, v112
	v_lshlrev_b32_e32 v112, 16, v233
	v_mul_f32_e32 v112, v234, v112
	v_cndmask_b32_e64 v235, v235, 1.0, s[28:29]
	v_mul_f32_e32 v50, v50, v112
	v_and_b32_e32 v112, 0xffff0000, v233
	v_mul_f32_e32 v112, v235, v112
	v_mul_f32_e32 v51, v51, v112
	v_or_b32_e32 v112, 48, v136
	v_mad_i64_i32 v[132:133], vcc, v112, s33, v[114:115]
	v_lshl_add_u64 v[134:135], v[132:133], 0, s[34:35]
	global_load_dwordx2 v[220:221], v[132:133], off
	global_load_dwordx2 v[222:223], v[134:135], off
	global_load_dwordx2 v[224:225], v[132:133], off offset:32
	global_load_dwordx2 v[226:227], v[134:135], off offset:32
	global_load_dwordx2 v[228:229], v[132:133], off offset:256
	global_load_dwordx2 v[230:231], v[134:135], off offset:256
	global_load_dwordx2 v[232:233], v[132:133], off offset:288
	global_load_dwordx2 v[234:235], v[134:135], off offset:288
	s_waitcnt vmcnt(14)
	v_lshlrev_b32_e32 v142, 16, v204
	v_lshlrev_b32_e32 v112, 16, v206
	v_max_f32_e32 v112, v112, v112
	v_max_f32_e32 v112, 0x219392ef, v112
	v_and_b32_e32 v137, 0xffff0000, v206
	v_rcp_f32_e32 v112, v112
	v_max_f32_e32 v137, v137, v137
	v_max_f32_e32 v137, 0x219392ef, v137
	v_lshlrev_b32_e32 v206, 16, v207
	v_rcp_f32_e32 v137, v137
	v_max_f32_e32 v206, v206, v206
	v_max_f32_e32 v206, 0x219392ef, v206
	v_and_b32_e32 v207, 0xffff0000, v207
	v_cndmask_b32_e64 v112, v112, 1.0, s[28:29]
	v_rcp_f32_e32 v206, v206
	v_max_f32_e32 v207, v207, v207
	v_max_f32_e32 v207, 0x219392ef, v207
	v_mul_f32_e32 v112, v112, v142
	v_cndmask_b32_e64 v137, v137, 1.0, s[28:29]
	v_rcp_f32_e32 v207, v207
	v_mul_f32_e32 v52, v52, v112
	v_and_b32_e32 v112, 0xffff0000, v204
	v_mul_f32_e32 v112, v137, v112
	v_cndmask_b32_e64 v206, v206, 1.0, s[28:29]
	v_mul_f32_e32 v53, v53, v112
	v_lshlrev_b32_e32 v112, 16, v205
	v_mul_f32_e32 v112, v206, v112
	v_cndmask_b32_e64 v207, v207, 1.0, s[28:29]
	v_mul_f32_e32 v54, v54, v112
	v_and_b32_e32 v112, 0xffff0000, v205
	v_mul_f32_e32 v112, v207, v112
	v_mul_f32_e32 v55, v55, v112
	s_waitcnt vmcnt(12)
	v_lshlrev_b32_e32 v142, 16, v208
	v_lshlrev_b32_e32 v112, 16, v210
	v_max_f32_e32 v112, v112, v112
	v_max_f32_e32 v112, 0x219392ef, v112
	v_and_b32_e32 v137, 0xffff0000, v210
	v_rcp_f32_e32 v112, v112
	v_max_f32_e32 v137, v137, v137
	v_max_f32_e32 v137, 0x219392ef, v137
	v_lshlrev_b32_e32 v210, 16, v211
	v_rcp_f32_e32 v137, v137
	v_max_f32_e32 v210, v210, v210
	v_max_f32_e32 v210, 0x219392ef, v210
	v_and_b32_e32 v211, 0xffff0000, v211
	v_cndmask_b32_e64 v112, v112, 1.0, s[28:29]
	v_rcp_f32_e32 v210, v210
	v_max_f32_e32 v211, v211, v211
	v_max_f32_e32 v211, 0x219392ef, v211
	v_mul_f32_e32 v112, v112, v142
	v_cndmask_b32_e64 v137, v137, 1.0, s[28:29]
	v_rcp_f32_e32 v211, v211
	v_mul_f32_e32 v56, v56, v112
	v_and_b32_e32 v112, 0xffff0000, v208
	v_mul_f32_e32 v112, v137, v112
	v_cndmask_b32_e64 v210, v210, 1.0, s[28:29]
	v_mul_f32_e32 v57, v57, v112
	v_lshlrev_b32_e32 v112, 16, v209
	v_mul_f32_e32 v112, v210, v112
	v_cndmask_b32_e64 v211, v211, 1.0, s[28:29]
	v_mul_f32_e32 v58, v58, v112
	v_and_b32_e32 v112, 0xffff0000, v209
	v_mul_f32_e32 v112, v211, v112
	v_mul_f32_e32 v59, v59, v112
	s_waitcnt vmcnt(10)
	v_lshlrev_b32_e32 v142, 16, v212
	v_lshlrev_b32_e32 v112, 16, v214
	v_max_f32_e32 v112, v112, v112
	v_max_f32_e32 v112, 0x219392ef, v112
	v_and_b32_e32 v137, 0xffff0000, v214
	v_rcp_f32_e32 v112, v112
	v_max_f32_e32 v137, v137, v137
	v_max_f32_e32 v137, 0x219392ef, v137
	v_lshlrev_b32_e32 v214, 16, v215
	v_rcp_f32_e32 v137, v137
	v_max_f32_e32 v214, v214, v214
	v_max_f32_e32 v214, 0x219392ef, v214
	v_and_b32_e32 v215, 0xffff0000, v215
	v_cndmask_b32_e64 v112, v112, 1.0, s[28:29]
	v_rcp_f32_e32 v214, v214
	v_max_f32_e32 v215, v215, v215
	v_max_f32_e32 v215, 0x219392ef, v215
	v_mul_f32_e32 v112, v112, v142
	v_cndmask_b32_e64 v137, v137, 1.0, s[28:29]
	v_rcp_f32_e32 v215, v215
	v_mul_f32_e32 v64, v64, v112
	v_and_b32_e32 v112, 0xffff0000, v212
	v_mul_f32_e32 v112, v137, v112
	v_cndmask_b32_e64 v214, v214, 1.0, s[28:29]
	v_mul_f32_e32 v65, v65, v112
	v_lshlrev_b32_e32 v112, 16, v213
	v_mul_f32_e32 v112, v214, v112
	v_cndmask_b32_e64 v215, v215, 1.0, s[28:29]
	v_mul_f32_e32 v66, v66, v112
	v_and_b32_e32 v112, 0xffff0000, v213
	v_mul_f32_e32 v112, v215, v112
	v_mul_f32_e32 v67, v67, v112
	s_waitcnt vmcnt(8)
; #define SBAR() __builtin_amdgcn_sched_barrier(0)
; DEVINL void phase_merge(const Params& p, int l, char* shm) {
;     ...
;       const int hoff = br < 2 ? 2048 : 0; const bool notlast = br < 2;
; #pragma unroll
;       for (int ai = 0; ai < 2; ++ai)
; #pragma unroll
;         for (int m = 0; m < 4; ++m) {
;           const u16* grow = MGT + (size_t)(brow + ai * 128 + wr * 64 + m * 16 + fr) * 6144 + br * 2048 + bcol + wc * 32 + fq * 4;
; #pragma unroll
;           for (int bj = 0; bj < 2; ++bj)
; #pragma unroll
;             for (int n = 0; n < 2; ++n) {
;               const u32x2 g = *reinterpret_cast<const u32x2*>(grow + bj * 128 + n * 16);
;               const u32x2 h = *reinterpret_cast<const u32x2*>(grow + hoff + bj * 128 + n * 16);
;               const float r0 = notlast ? __builtin_amdgcn_rcpf(fmaxf(__uint_as_float(h[0] << 16), 1e-18f)) : 1.f;
;               const float r1 = notlast ? __builtin_amdgcn_rcpf(fmaxf(__uint_as_float(h[0] & 0xffff0000u), 1e-18f)) : 1.f;
;               const float r2 = notlast ? __builtin_amdgcn_rcpf(fmaxf(__uint_as_float(h[1] << 16), 1e-18f)) : 1.f;
;               const float r3 = notlast ? __builtin_amdgcn_rcpf(fmaxf(__uint_as_float(h[1] & 0xffff0000u), 1e-18f)) : 1.f;
;               acc[ai][bj][m][n][0] *= __uint_as_float(g[0] << 16) * r0; acc[ai][bj][m][n][1] *= __uint_as_float(g[0] & 0xffff0000u) * r1;
;               acc[ai][bj][m][n][2] *= __uint_as_float(g[1] << 16) * r2; acc[ai][bj][m][n][3] *= __uint_as_float(g[1] & 0xffff0000u) * r3;
;             }
;           SBAR();
;         }
	v_lshlrev_b32_e32 v142, 16, v216
	v_lshlrev_b32_e32 v112, 16, v218
	v_max_f32_e32 v112, v112, v112
	v_max_f32_e32 v112, 0x219392ef, v112
	v_and_b32_e32 v137, 0xffff0000, v218
	v_rcp_f32_e32 v112, v112
	v_max_f32_e32 v137, v137, v137
	v_max_f32_e32 v137, 0x219392ef, v137
	v_lshlrev_b32_e32 v218, 16, v219
	v_rcp_f32_e32 v137, v137
	v_max_f32_e32 v218, v218, v218
	v_max_f32_e32 v218, 0x219392ef, v218
	v_and_b32_e32 v219, 0xffff0000, v219
	v_cndmask_b32_e64 v112, v112, 1.0, s[28:29]
	v_rcp_f32_e32 v218, v218
	v_max_f32_e32 v219, v219, v219
	v_max_f32_e32 v219, 0x219392ef, v219
	v_mul_f32_e32 v112, v112, v142
	v_cndmask_b32_e64 v137, v137, 1.0, s[28:29]
	v_rcp_f32_e32 v219, v219
	v_mul_f32_e32 v80, v80, v112
	v_and_b32_e32 v112, 0xffff0000, v216
	v_mul_f32_e32 v112, v137, v112
	v_cndmask_b32_e64 v218, v218, 1.0, s[28:29]
	v_mul_f32_e32 v81, v81, v112
	v_lshlrev_b32_e32 v112, 16, v217
	v_mul_f32_e32 v112, v218, v112
	v_cndmask_b32_e64 v219, v219, 1.0, s[28:29]
	v_mul_f32_e32 v82, v82, v112
	v_and_b32_e32 v112, 0xffff0000, v217
	v_mul_f32_e32 v112, v219, v112
	v_mul_f32_e32 v83, v83, v112
	v_add_u32_e32 v112, 0x80, v136
	v_mad_i64_i32 v[132:133], vcc, v112, s33, v[114:115]
	v_lshl_add_u64 v[134:135], v[132:133], 0, s[34:35]
	global_load_dwordx2 v[204:205], v[132:133], off
	global_load_dwordx2 v[206:207], v[134:135], off
	global_load_dwordx2 v[208:209], v[132:133], off offset:32
	global_load_dwordx2 v[210:211], v[134:135], off offset:32
	global_load_dwordx2 v[212:213], v[132:133], off offset:256
	global_load_dwordx2 v[214:215], v[134:135], off offset:256
	global_load_dwordx2 v[216:217], v[132:133], off offset:288
	global_load_dwordx2 v[218:219], v[134:135], off offset:288
	s_waitcnt vmcnt(14)
	v_lshlrev_b32_e32 v142, 16, v220
	v_lshlrev_b32_e32 v112, 16, v222
	v_max_f32_e32 v112, v112, v112
	v_max_f32_e32 v112, 0x219392ef, v112
	v_and_b32_e32 v137, 0xffff0000, v222
	v_rcp_f32_e32 v112, v112
	v_max_f32_e32 v137, v137, v137
	v_max_f32_e32 v137, 0x219392ef, v137
	v_lshlrev_b32_e32 v222, 16, v223
	v_rcp_f32_e32 v137, v137
	v_max_f32_e32 v222, v222, v222
	v_max_f32_e32 v222, 0x219392ef, v222
	v_and_b32_e32 v223, 0xffff0000, v223
	v_cndmask_b32_e64 v112, v112, 1.0, s[28:29]
	v_rcp_f32_e32 v222, v222
	v_max_f32_e32 v223, v223, v223
	v_max_f32_e32 v223, 0x219392ef, v223
	v_mul_f32_e32 v112, v112, v142
	v_cndmask_b32_e64 v137, v137, 1.0, s[28:29]
	v_rcp_f32_e32 v223, v223
	v_mul_f32_e32 v84, v84, v112
	v_and_b32_e32 v112, 0xffff0000, v220
	v_mul_f32_e32 v112, v137, v112
	v_cndmask_b32_e64 v222, v222, 1.0, s[28:29]
	v_mul_f32_e32 v85, v85, v112
	v_lshlrev_b32_e32 v112, 16, v221
	v_mul_f32_e32 v112, v222, v112
	v_cndmask_b32_e64 v223, v223, 1.0, s[28:29]
	v_mul_f32_e32 v86, v86, v112
	v_and_b32_e32 v112, 0xffff0000, v221
	v_mul_f32_e32 v112, v223, v112
	v_mul_f32_e32 v87, v87, v112
	s_waitcnt vmcnt(12)
	v_lshlrev_b32_e32 v142, 16, v224
	v_lshlrev_b32_e32 v112, 16, v226
	v_max_f32_e32 v112, v112, v112
	v_max_f32_e32 v112, 0x219392ef, v112
	v_and_b32_e32 v137, 0xffff0000, v226
	v_rcp_f32_e32 v112, v112
	v_max_f32_e32 v137, v137, v137
	v_max_f32_e32 v137, 0x219392ef, v137
	v_lshlrev_b32_e32 v226, 16, v227
	v_rcp_f32_e32 v137, v137
	v_max_f32_e32 v226, v226, v226
	v_max_f32_e32 v226, 0x219392ef, v226
	v_and_b32_e32 v227, 0xffff0000, v227
	v_cndmask_b32_e64 v112, v112, 1.0, s[28:29]
	v_rcp_f32_e32 v226, v226
	v_max_f32_e32 v227, v227, v227
	v_max_f32_e32 v227, 0x219392ef, v227
	v_mul_f32_e32 v112, v112, v142
	v_cndmask_b32_e64 v137, v137, 1.0, s[28:29]
	v_rcp_f32_e32 v227, v227
	v_mul_f32_e32 v88, v88, v112
	v_and_b32_e32 v112, 0xffff0000, v224
	v_mul_f32_e32 v112, v137, v112
	v_cndmask_b32_e64 v226, v226, 1.0, s[28:29]
	v_mul_f32_e32 v89, v89, v112
	v_lshlrev_b32_e32 v112, 16, v225
	v_mul_f32_e32 v112, v226, v112
	v_cndmask_b32_e64 v227, v227, 1.0, s[28:29]
	v_mul_f32_e32 v90, v90, v112
	v_and_b32_e32 v112, 0xffff0000, v225
	v_mul_f32_e32 v112, v227, v112
	v_mul_f32_e32 v91, v91, v112
	s_waitcnt vmcnt(10)
	v_lshlrev_b32_e32 v142, 16, v228
	v_lshlrev_b32_e32 v112, 16, v230
	v_max_f32_e32 v112, v112, v112
	v_max_f32_e32 v112, 0x219392ef, v112
	v_and_b32_e32 v137, 0xffff0000, v230
	v_rcp_f32_e32 v112, v112
	v_max_f32_e32 v137, v137, v137
	v_max_f32_e32 v137, 0x219392ef, v137
	v_lshlrev_b32_e32 v230, 16, v231
	v_rcp_f32_e32 v137, v137
	v_max_f32_e32 v230, v230, v230
	v_max_f32_e32 v230, 0x219392ef, v230
	v_and_b32_e32 v231, 0xffff0000, v231
	v_cndmask_b32_e64 v112, v112, 1.0, s[28:29]
	v_rcp_f32_e32 v230, v230
	v_max_f32_e32 v231, v231, v231
	v_max_f32_e32 v231, 0x219392ef, v231
	v_mul_f32_e32 v112, v112, v142
	v_cndmask_b32_e64 v137, v137, 1.0, s[28:29]
	v_rcp_f32_e32 v231, v231
	v_mul_f32_e32 v96, v96, v112
	v_and_b32_e32 v112, 0xffff0000, v228
	v_mul_f32_e32 v112, v137, v112
	v_cndmask_b32_e64 v230, v230, 1.0, s[28:29]
	v_mul_f32_e32 v97, v97, v112
	v_lshlrev_b32_e32 v112, 16, v229
	v_mul_f32_e32 v112, v230, v112
	v_cndmask_b32_e64 v231, v231, 1.0, s[28:29]
	v_mul_f32_e32 v98, v98, v112
	v_and_b32_e32 v112, 0xffff0000, v229
	v_mul_f32_e32 v112, v231, v112
	v_mul_f32_e32 v99, v99, v112
	s_waitcnt vmcnt(8)
; #define SBAR() __builtin_amdgcn_sched_barrier(0)
; DEVINL void phase_merge(const Params& p, int l, char* shm) {
;     ...
;       const int hoff = br < 2 ? 2048 : 0; const bool notlast = br < 2;
; #pragma unroll
;       for (int ai = 0; ai < 2; ++ai)
; #pragma unroll
;         for (int m = 0; m < 4; ++m) {
;           const u16* grow = MGT + (size_t)(brow + ai * 128 + wr * 64 + m * 16 + fr) * 6144 + br * 2048 + bcol + wc * 32 + fq * 4;
; #pragma unroll
;           for (int bj = 0; bj < 2; ++bj)
; #pragma unroll
;             for (int n = 0; n < 2; ++n) {
;               const u32x2 g = *reinterpret_cast<const u32x2*>(grow + bj * 128 + n * 16);
;               const u32x2 h = *reinterpret_cast<const u32x2*>(grow + hoff + bj * 128 + n * 16);
;               const float r0 = notlast ? __builtin_amdgcn_rcpf(fmaxf(__uint_as_float(h[0] << 16), 1e-18f)) : 1.f;
;               const float r1 = notlast ? __builtin_amdgcn_rcpf(fmaxf(__uint_as_float(h[0] & 0xffff0000u), 1e-18f)) : 1.f;
;               const float r2 = notlast ? __builtin_amdgcn_rcpf(fmaxf(__uint_as_float(h[1] << 16), 1e-18f)) : 1.f;
;               const float r3 = notlast ? __builtin_amdgcn_rcpf(fmaxf(__uint_as_float(h[1] & 0xffff0000u), 1e-18f)) : 1.f;
;               acc[ai][bj][m][n][0] *= __uint_as_float(g[0] << 16) * r0; acc[ai][bj][m][n][1] *= __uint_as_float(g[0] & 0xffff0000u) * r1;
;               acc[ai][bj][m][n][2] *= __uint_as_float(g[1] << 16) * r2; acc[ai][bj][m][n][3] *= __uint_as_float(g[1] & 0xffff0000u) * r3;
;             }
;           SBAR();
;         }
	v_lshlrev_b32_e32 v142, 16, v232
	v_lshlrev_b32_e32 v112, 16, v234
	v_max_f32_e32 v112, v112, v112
	v_max_f32_e32 v112, 0x219392ef, v112
	v_and_b32_e32 v137, 0xffff0000, v234
	v_rcp_f32_e32 v112, v112
	v_max_f32_e32 v137, v137, v137
	v_max_f32_e32 v137, 0x219392ef, v137
	v_lshlrev_b32_e32 v234, 16, v235
	v_rcp_f32_e32 v137, v137
	v_max_f32_e32 v234, v234, v234
	v_max_f32_e32 v234, 0x219392ef, v234
	v_and_b32_e32 v235, 0xffff0000, v235
	v_cndmask_b32_e64 v112, v112, 1.0, s[28:29]
	v_rcp_f32_e32 v234, v234
	v_max_f32_e32 v235, v235, v235
	v_max_f32_e32 v235, 0x219392ef, v235
	v_mul_f32_e32 v112, v112, v142
	v_cndmask_b32_e64 v137, v137, 1.0, s[28:29]
	v_rcp_f32_e32 v235, v235
	v_mul_f32_e32 v116, v116, v112
	v_and_b32_e32 v112, 0xffff0000, v232
	v_mul_f32_e32 v112, v137, v112
	v_cndmask_b32_e64 v234, v234, 1.0, s[28:29]
	v_mul_f32_e32 v117, v117, v112
	v_lshlrev_b32_e32 v112, 16, v233
	v_mul_f32_e32 v112, v234, v112
	v_cndmask_b32_e64 v235, v235, 1.0, s[28:29]
	v_mul_f32_e32 v118, v118, v112
	v_and_b32_e32 v112, 0xffff0000, v233
	v_mul_f32_e32 v112, v235, v112
	v_mul_f32_e32 v119, v119, v112
	v_add_u32_e32 v112, 0x90, v136
	v_mad_i64_i32 v[132:133], vcc, v112, s33, v[114:115]
	v_lshl_add_u64 v[134:135], v[132:133], 0, s[34:35]
	global_load_dwordx2 v[220:221], v[132:133], off
	global_load_dwordx2 v[222:223], v[134:135], off
	global_load_dwordx2 v[224:225], v[132:133], off offset:32
	global_load_dwordx2 v[226:227], v[134:135], off offset:32
	global_load_dwordx2 v[228:229], v[132:133], off offset:256
	global_load_dwordx2 v[230:231], v[134:135], off offset:256
	global_load_dwordx2 v[232:233], v[132:133], off offset:288
	global_load_dwordx2 v[234:235], v[134:135], off offset:288
	s_waitcnt vmcnt(14)
	v_lshlrev_b32_e32 v142, 16, v204
	v_lshlrev_b32_e32 v112, 16, v206
	v_max_f32_e32 v112, v112, v112
	v_max_f32_e32 v112, 0x219392ef, v112
	v_and_b32_e32 v137, 0xffff0000, v206
	v_rcp_f32_e32 v112, v112
	v_max_f32_e32 v137, v137, v137
	v_max_f32_e32 v137, 0x219392ef, v137
	v_lshlrev_b32_e32 v206, 16, v207
	v_rcp_f32_e32 v137, v137
	v_max_f32_e32 v206, v206, v206
	v_max_f32_e32 v206, 0x219392ef, v206
	v_and_b32_e32 v207, 0xffff0000, v207
	v_cndmask_b32_e64 v112, v112, 1.0, s[28:29]
	v_rcp_f32_e32 v206, v206
	v_max_f32_e32 v207, v207, v207
	v_max_f32_e32 v207, 0x219392ef, v207
	v_mul_f32_e32 v112, v112, v142
	v_cndmask_b32_e64 v137, v137, 1.0, s[28:29]
	v_rcp_f32_e32 v207, v207
	v_mul_f32_e32 v120, v120, v112
	v_and_b32_e32 v112, 0xffff0000, v204
	v_mul_f32_e32 v112, v137, v112
	v_cndmask_b32_e64 v206, v206, 1.0, s[28:29]
	v_mul_f32_e32 v121, v121, v112
	v_lshlrev_b32_e32 v112, 16, v205
	v_mul_f32_e32 v112, v206, v112
	v_cndmask_b32_e64 v207, v207, 1.0, s[28:29]
	v_mul_f32_e32 v122, v122, v112
	v_and_b32_e32 v112, 0xffff0000, v205
	v_mul_f32_e32 v112, v207, v112
	v_mul_f32_e32 v123, v123, v112
	s_waitcnt vmcnt(12)
	v_lshlrev_b32_e32 v142, 16, v208
	v_lshlrev_b32_e32 v112, 16, v210
	v_max_f32_e32 v112, v112, v112
	v_max_f32_e32 v112, 0x219392ef, v112
	v_and_b32_e32 v137, 0xffff0000, v210
	v_rcp_f32_e32 v112, v112
	v_max_f32_e32 v137, v137, v137
	v_max_f32_e32 v137, 0x219392ef, v137
	v_lshlrev_b32_e32 v210, 16, v211
	v_rcp_f32_e32 v137, v137
	v_max_f32_e32 v210, v210, v210
	v_max_f32_e32 v210, 0x219392ef, v210
	v_and_b32_e32 v211, 0xffff0000, v211
	v_cndmask_b32_e64 v112, v112, 1.0, s[28:29]
	v_rcp_f32_e32 v210, v210
	v_max_f32_e32 v211, v211, v211
	v_max_f32_e32 v211, 0x219392ef, v211
	v_mul_f32_e32 v112, v112, v142
	v_cndmask_b32_e64 v137, v137, 1.0, s[28:29]
	v_rcp_f32_e32 v211, v211
	v_mul_f32_e32 v124, v124, v112
	v_and_b32_e32 v112, 0xffff0000, v208
	v_mul_f32_e32 v112, v137, v112
	v_cndmask_b32_e64 v210, v210, 1.0, s[28:29]
	v_mul_f32_e32 v125, v125, v112
	v_lshlrev_b32_e32 v112, 16, v209
	v_mul_f32_e32 v112, v210, v112
	v_cndmask_b32_e64 v211, v211, 1.0, s[28:29]
	v_mul_f32_e32 v126, v126, v112
	v_and_b32_e32 v112, 0xffff0000, v209
	v_mul_f32_e32 v112, v211, v112
	v_mul_f32_e32 v127, v127, v112
	s_waitcnt vmcnt(10)
	v_lshlrev_b32_e32 v142, 16, v212
	v_lshlrev_b32_e32 v112, 16, v214
	v_max_f32_e32 v112, v112, v112
	v_max_f32_e32 v112, 0x219392ef, v112
	v_and_b32_e32 v137, 0xffff0000, v214
	v_rcp_f32_e32 v112, v112
	v_max_f32_e32 v137, v137, v137
	v_max_f32_e32 v137, 0x219392ef, v137
	v_lshlrev_b32_e32 v214, 16, v215
	v_rcp_f32_e32 v137, v137
	v_max_f32_e32 v214, v214, v214
	v_max_f32_e32 v214, 0x219392ef, v214
	v_and_b32_e32 v215, 0xffff0000, v215
	v_cndmask_b32_e64 v112, v112, 1.0, s[28:29]
	v_rcp_f32_e32 v214, v214
	v_max_f32_e32 v215, v215, v215
	v_max_f32_e32 v215, 0x219392ef, v215
	v_mul_f32_e32 v112, v112, v142
	v_cndmask_b32_e64 v137, v137, 1.0, s[28:29]
	v_rcp_f32_e32 v215, v215
	v_mul_f32_e32 v128, v128, v112
	v_and_b32_e32 v112, 0xffff0000, v212
	v_mul_f32_e32 v112, v137, v112
	v_cndmask_b32_e64 v214, v214, 1.0, s[28:29]
	v_mul_f32_e32 v129, v129, v112
	v_lshlrev_b32_e32 v112, 16, v213
	v_mul_f32_e32 v112, v214, v112
	v_cndmask_b32_e64 v215, v215, 1.0, s[28:29]
	v_mul_f32_e32 v130, v130, v112
	v_and_b32_e32 v112, 0xffff0000, v213
	v_mul_f32_e32 v112, v215, v112
	v_mul_f32_e32 v131, v131, v112
	s_waitcnt vmcnt(8)
; #define SBAR() __builtin_amdgcn_sched_barrier(0)
; DEVINL void phase_merge(const Params& p, int l, char* shm) {
;     ...
;       const int hoff = br < 2 ? 2048 : 0; const bool notlast = br < 2;
; #pragma unroll
;       for (int ai = 0; ai < 2; ++ai)
; #pragma unroll
;         for (int m = 0; m < 4; ++m) {
;           const u16* grow = MGT + (size_t)(brow + ai * 128 + wr * 64 + m * 16 + fr) * 6144 + br * 2048 + bcol + wc * 32 + fq * 4;
; #pragma unroll
;           for (int bj = 0; bj < 2; ++bj)
; #pragma unroll
;             for (int n = 0; n < 2; ++n) {
;               const u32x2 g = *reinterpret_cast<const u32x2*>(grow + bj * 128 + n * 16);
;               const u32x2 h = *reinterpret_cast<const u32x2*>(grow + hoff + bj * 128 + n * 16);
;               const float r0 = notlast ? __builtin_amdgcn_rcpf(fmaxf(__uint_as_float(h[0] << 16), 1e-18f)) : 1.f;
;               const float r1 = notlast ? __builtin_amdgcn_rcpf(fmaxf(__uint_as_float(h[0] & 0xffff0000u), 1e-18f)) : 1.f;
;               const float r2 = notlast ? __builtin_amdgcn_rcpf(fmaxf(__uint_as_float(h[1] << 16), 1e-18f)) : 1.f;
;               const float r3 = notlast ? __builtin_amdgcn_rcpf(fmaxf(__uint_as_float(h[1] & 0xffff0000u), 1e-18f)) : 1.f;
;               acc[ai][bj][m][n][0] *= __uint_as_float(g[0] << 16) * r0; acc[ai][bj][m][n][1] *= __uint_as_float(g[0] & 0xffff0000u) * r1;
;               acc[ai][bj][m][n][2] *= __uint_as_float(g[1] << 16) * r2; acc[ai][bj][m][n][3] *= __uint_as_float(g[1] & 0xffff0000u) * r3;
;             }
;           SBAR();
;         }
	v_lshlrev_b32_e32 v142, 16, v216
	v_lshlrev_b32_e32 v112, 16, v218
	v_max_f32_e32 v112, v112, v112
	v_max_f32_e32 v112, 0x219392ef, v112
	v_and_b32_e32 v137, 0xffff0000, v218
	v_rcp_f32_e32 v112, v112
	v_max_f32_e32 v137, v137, v137
	v_max_f32_e32 v137, 0x219392ef, v137
	v_lshlrev_b32_e32 v218, 16, v219
	v_rcp_f32_e32 v137, v137
	v_max_f32_e32 v218, v218, v218
	v_max_f32_e32 v218, 0x219392ef, v218
	v_and_b32_e32 v219, 0xffff0000, v219
	v_cndmask_b32_e64 v112, v112, 1.0, s[28:29]
	v_rcp_f32_e32 v218, v218
	v_max_f32_e32 v219, v219, v219
	v_max_f32_e32 v219, 0x219392ef, v219
	v_mul_f32_e32 v112, v112, v142
	v_cndmask_b32_e64 v137, v137, 1.0, s[28:29]
	v_rcp_f32_e32 v219, v219
	v_mul_f32_e32 v108, v108, v112
	v_and_b32_e32 v112, 0xffff0000, v216
	v_mul_f32_e32 v112, v137, v112
	v_cndmask_b32_e64 v218, v218, 1.0, s[28:29]
	v_mul_f32_e32 v109, v109, v112
	v_lshlrev_b32_e32 v112, 16, v217
	v_mul_f32_e32 v112, v218, v112
	v_cndmask_b32_e64 v219, v219, 1.0, s[28:29]
	v_mul_f32_e32 v110, v110, v112
	v_and_b32_e32 v112, 0xffff0000, v217
	v_mul_f32_e32 v112, v219, v112
	v_mul_f32_e32 v111, v111, v112
	v_add_u32_e32 v112, 0xa0, v136
	v_mad_i64_i32 v[132:133], vcc, v112, s33, v[114:115]
	v_lshl_add_u64 v[134:135], v[132:133], 0, s[34:35]
	global_load_dwordx2 v[204:205], v[132:133], off
	global_load_dwordx2 v[206:207], v[134:135], off
	global_load_dwordx2 v[208:209], v[132:133], off offset:32
	global_load_dwordx2 v[210:211], v[134:135], off offset:32
	global_load_dwordx2 v[212:213], v[132:133], off offset:256
	global_load_dwordx2 v[214:215], v[134:135], off offset:256
	global_load_dwordx2 v[216:217], v[132:133], off offset:288
	global_load_dwordx2 v[218:219], v[134:135], off offset:288
	s_waitcnt vmcnt(14)
	v_lshlrev_b32_e32 v142, 16, v220
	v_lshlrev_b32_e32 v112, 16, v222
	v_max_f32_e32 v112, v112, v112
	v_max_f32_e32 v112, 0x219392ef, v112
	v_and_b32_e32 v137, 0xffff0000, v222
	v_rcp_f32_e32 v112, v112
	v_max_f32_e32 v137, v137, v137
	v_max_f32_e32 v137, 0x219392ef, v137
	v_lshlrev_b32_e32 v222, 16, v223
	v_rcp_f32_e32 v137, v137
	v_max_f32_e32 v222, v222, v222
	v_max_f32_e32 v222, 0x219392ef, v222
	v_and_b32_e32 v223, 0xffff0000, v223
	v_cndmask_b32_e64 v112, v112, 1.0, s[28:29]
	v_rcp_f32_e32 v222, v222
	v_max_f32_e32 v223, v223, v223
	v_max_f32_e32 v223, 0x219392ef, v223
	v_mul_f32_e32 v112, v112, v142
	v_cndmask_b32_e64 v137, v137, 1.0, s[28:29]
	v_rcp_f32_e32 v223, v223
	v_mul_f32_e32 v104, v104, v112
	v_and_b32_e32 v112, 0xffff0000, v220
	v_mul_f32_e32 v112, v137, v112
	v_cndmask_b32_e64 v222, v222, 1.0, s[28:29]
	v_mul_f32_e32 v105, v105, v112
	v_lshlrev_b32_e32 v112, 16, v221
	v_mul_f32_e32 v112, v222, v112
	v_cndmask_b32_e64 v223, v223, 1.0, s[28:29]
	v_mul_f32_e32 v106, v106, v112
	v_and_b32_e32 v112, 0xffff0000, v221
	v_mul_f32_e32 v112, v223, v112
	v_mul_f32_e32 v107, v107, v112
	s_waitcnt vmcnt(12)
	v_lshlrev_b32_e32 v142, 16, v224
	v_lshlrev_b32_e32 v112, 16, v226
	v_max_f32_e32 v112, v112, v112
	v_max_f32_e32 v112, 0x219392ef, v112
	v_and_b32_e32 v137, 0xffff0000, v226
	v_rcp_f32_e32 v112, v112
	v_max_f32_e32 v137, v137, v137
	v_max_f32_e32 v137, 0x219392ef, v137
	v_lshlrev_b32_e32 v226, 16, v227
	v_rcp_f32_e32 v137, v137
	v_max_f32_e32 v226, v226, v226
	v_max_f32_e32 v226, 0x219392ef, v226
	v_and_b32_e32 v227, 0xffff0000, v227
	v_cndmask_b32_e64 v112, v112, 1.0, s[28:29]
	v_rcp_f32_e32 v226, v226
	v_max_f32_e32 v227, v227, v227
	v_max_f32_e32 v227, 0x219392ef, v227
	v_mul_f32_e32 v112, v112, v142
	v_cndmask_b32_e64 v137, v137, 1.0, s[28:29]
	v_rcp_f32_e32 v227, v227
	v_mul_f32_e32 v100, v100, v112
	v_and_b32_e32 v112, 0xffff0000, v224
	v_mul_f32_e32 v112, v137, v112
	v_cndmask_b32_e64 v226, v226, 1.0, s[28:29]
	v_mul_f32_e32 v101, v101, v112
	v_lshlrev_b32_e32 v112, 16, v225
	v_mul_f32_e32 v112, v226, v112
	v_cndmask_b32_e64 v227, v227, 1.0, s[28:29]
	v_mul_f32_e32 v102, v102, v112
	v_and_b32_e32 v112, 0xffff0000, v225
	v_mul_f32_e32 v112, v227, v112
	v_mul_f32_e32 v103, v103, v112
	s_waitcnt vmcnt(10)
	v_lshlrev_b32_e32 v142, 16, v228
	v_lshlrev_b32_e32 v112, 16, v230
	v_max_f32_e32 v112, v112, v112
	v_max_f32_e32 v112, 0x219392ef, v112
	v_and_b32_e32 v137, 0xffff0000, v230
	v_rcp_f32_e32 v112, v112
	v_max_f32_e32 v137, v137, v137
	v_max_f32_e32 v137, 0x219392ef, v137
	v_lshlrev_b32_e32 v230, 16, v231
	v_rcp_f32_e32 v137, v137
	v_max_f32_e32 v230, v230, v230
	v_max_f32_e32 v230, 0x219392ef, v230
	v_and_b32_e32 v231, 0xffff0000, v231
	v_cndmask_b32_e64 v112, v112, 1.0, s[28:29]
	v_rcp_f32_e32 v230, v230
	v_max_f32_e32 v231, v231, v231
	v_max_f32_e32 v231, 0x219392ef, v231
	v_mul_f32_e32 v112, v112, v142
	v_cndmask_b32_e64 v137, v137, 1.0, s[28:29]
	v_rcp_f32_e32 v231, v231
	v_mul_f32_e32 v92, v92, v112
	v_and_b32_e32 v112, 0xffff0000, v228
	v_mul_f32_e32 v112, v137, v112
	v_cndmask_b32_e64 v230, v230, 1.0, s[28:29]
	v_mul_f32_e32 v93, v93, v112
	v_lshlrev_b32_e32 v112, 16, v229
	v_mul_f32_e32 v112, v230, v112
	v_cndmask_b32_e64 v231, v231, 1.0, s[28:29]
	v_mul_f32_e32 v94, v94, v112
	v_and_b32_e32 v112, 0xffff0000, v229
	v_mul_f32_e32 v112, v231, v112
	v_mul_f32_e32 v95, v95, v112
	s_waitcnt vmcnt(8)
; #define SBAR() __builtin_amdgcn_sched_barrier(0)
; DEVINL void phase_merge(const Params& p, int l, char* shm) {
;     ...
;       const int hoff = br < 2 ? 2048 : 0; const bool notlast = br < 2;
; #pragma unroll
;       for (int ai = 0; ai < 2; ++ai)
; #pragma unroll
;         for (int m = 0; m < 4; ++m) {
;           const u16* grow = MGT + (size_t)(brow + ai * 128 + wr * 64 + m * 16 + fr) * 6144 + br * 2048 + bcol + wc * 32 + fq * 4;
; #pragma unroll
;           for (int bj = 0; bj < 2; ++bj)
; #pragma unroll
;             for (int n = 0; n < 2; ++n) {
;               const u32x2 g = *reinterpret_cast<const u32x2*>(grow + bj * 128 + n * 16);
;               const u32x2 h = *reinterpret_cast<const u32x2*>(grow + hoff + bj * 128 + n * 16);
;               const float r0 = notlast ? __builtin_amdgcn_rcpf(fmaxf(__uint_as_float(h[0] << 16), 1e-18f)) : 1.f;
;               const float r1 = notlast ? __builtin_amdgcn_rcpf(fmaxf(__uint_as_float(h[0] & 0xffff0000u), 1e-18f)) : 1.f;
;               const float r2 = notlast ? __builtin_amdgcn_rcpf(fmaxf(__uint_as_float(h[1] << 16), 1e-18f)) : 1.f;
;               const float r3 = notlast ? __builtin_amdgcn_rcpf(fmaxf(__uint_as_float(h[1] & 0xffff0000u), 1e-18f)) : 1.f;
;               acc[ai][bj][m][n][0] *= __uint_as_float(g[0] << 16) * r0; acc[ai][bj][m][n][1] *= __uint_as_float(g[0] & 0xffff0000u) * r1;
;               acc[ai][bj][m][n][2] *= __uint_as_float(g[1] << 16) * r2; acc[ai][bj][m][n][3] *= __uint_as_float(g[1] & 0xffff0000u) * r3;
;             }
;           SBAR();
;         }
	v_lshlrev_b32_e32 v142, 16, v232
	v_lshlrev_b32_e32 v112, 16, v234
	v_max_f32_e32 v112, v112, v112
	v_max_f32_e32 v112, 0x219392ef, v112
	v_and_b32_e32 v137, 0xffff0000, v234
	v_rcp_f32_e32 v112, v112
	v_max_f32_e32 v137, v137, v137
	v_max_f32_e32 v137, 0x219392ef, v137
	v_lshlrev_b32_e32 v234, 16, v235
	v_rcp_f32_e32 v137, v137
	v_max_f32_e32 v234, v234, v234
	v_max_f32_e32 v234, 0x219392ef, v234
	v_and_b32_e32 v235, 0xffff0000, v235
	v_cndmask_b32_e64 v112, v112, 1.0, s[28:29]
	v_rcp_f32_e32 v234, v234
	v_max_f32_e32 v235, v235, v235
	v_max_f32_e32 v235, 0x219392ef, v235
	v_mul_f32_e32 v112, v112, v142
	v_cndmask_b32_e64 v137, v137, 1.0, s[28:29]
	v_rcp_f32_e32 v235, v235
	v_mul_f32_e32 v76, v76, v112
	v_and_b32_e32 v112, 0xffff0000, v232
	v_mul_f32_e32 v112, v137, v112
	v_cndmask_b32_e64 v234, v234, 1.0, s[28:29]
	v_mul_f32_e32 v77, v77, v112
	v_lshlrev_b32_e32 v112, 16, v233
	v_mul_f32_e32 v112, v234, v112
	v_cndmask_b32_e64 v235, v235, 1.0, s[28:29]
	v_mul_f32_e32 v78, v78, v112
	v_and_b32_e32 v112, 0xffff0000, v233
	v_mul_f32_e32 v112, v235, v112
	v_mul_f32_e32 v79, v79, v112
	v_add_u32_e32 v112, 0xb0, v136
	v_mad_i64_i32 v[132:133], vcc, v112, s33, v[114:115]
	v_lshl_add_u64 v[134:135], v[132:133], 0, s[34:35]
	global_load_dwordx2 v[220:221], v[132:133], off
	global_load_dwordx2 v[222:223], v[134:135], off
	global_load_dwordx2 v[224:225], v[132:133], off offset:32
	global_load_dwordx2 v[226:227], v[134:135], off offset:32
	global_load_dwordx2 v[228:229], v[132:133], off offset:256
	global_load_dwordx2 v[230:231], v[134:135], off offset:256
	global_load_dwordx2 v[232:233], v[132:133], off offset:288
	global_load_dwordx2 v[234:235], v[134:135], off offset:288
	s_waitcnt vmcnt(14)
	v_lshlrev_b32_e32 v142, 16, v204
	v_lshlrev_b32_e32 v112, 16, v206
	v_max_f32_e32 v112, v112, v112
	v_max_f32_e32 v112, 0x219392ef, v112
	v_and_b32_e32 v137, 0xffff0000, v206
	v_rcp_f32_e32 v112, v112
	v_max_f32_e32 v137, v137, v137
	v_max_f32_e32 v137, 0x219392ef, v137
	v_lshlrev_b32_e32 v206, 16, v207
	v_rcp_f32_e32 v137, v137
	v_max_f32_e32 v206, v206, v206
	v_max_f32_e32 v206, 0x219392ef, v206
	v_and_b32_e32 v207, 0xffff0000, v207
	v_cndmask_b32_e64 v112, v112, 1.0, s[28:29]
	v_rcp_f32_e32 v206, v206
	v_max_f32_e32 v207, v207, v207
	v_max_f32_e32 v207, 0x219392ef, v207
	v_mul_f32_e32 v112, v112, v142
	v_cndmask_b32_e64 v137, v137, 1.0, s[28:29]
	v_rcp_f32_e32 v207, v207
	v_mul_f32_e32 v72, v72, v112
	v_and_b32_e32 v112, 0xffff0000, v204
	v_mul_f32_e32 v112, v137, v112
	v_cndmask_b32_e64 v206, v206, 1.0, s[28:29]
	v_mul_f32_e32 v73, v73, v112
	v_lshlrev_b32_e32 v112, 16, v205
	v_mul_f32_e32 v112, v206, v112
	v_cndmask_b32_e64 v207, v207, 1.0, s[28:29]
	v_mul_f32_e32 v74, v74, v112
	v_and_b32_e32 v112, 0xffff0000, v205
	v_mul_f32_e32 v112, v207, v112
	v_mul_f32_e32 v75, v75, v112
	s_waitcnt vmcnt(12)
	v_lshlrev_b32_e32 v142, 16, v208
	v_lshlrev_b32_e32 v112, 16, v210
	v_max_f32_e32 v112, v112, v112
	v_max_f32_e32 v112, 0x219392ef, v112
	v_and_b32_e32 v137, 0xffff0000, v210
	v_rcp_f32_e32 v112, v112
	v_max_f32_e32 v137, v137, v137
	v_max_f32_e32 v137, 0x219392ef, v137
	v_lshlrev_b32_e32 v210, 16, v211
	v_rcp_f32_e32 v137, v137
	v_max_f32_e32 v210, v210, v210
	v_max_f32_e32 v210, 0x219392ef, v210
	v_and_b32_e32 v211, 0xffff0000, v211
	v_cndmask_b32_e64 v112, v112, 1.0, s[28:29]
	v_rcp_f32_e32 v210, v210
	v_max_f32_e32 v211, v211, v211
	v_max_f32_e32 v211, 0x219392ef, v211
	v_mul_f32_e32 v112, v112, v142
	v_cndmask_b32_e64 v137, v137, 1.0, s[28:29]
	v_rcp_f32_e32 v211, v211
	v_mul_f32_e32 v68, v68, v112
	v_and_b32_e32 v112, 0xffff0000, v208
	v_mul_f32_e32 v112, v137, v112
	v_cndmask_b32_e64 v210, v210, 1.0, s[28:29]
	v_mul_f32_e32 v69, v69, v112
	v_lshlrev_b32_e32 v112, 16, v209
	v_mul_f32_e32 v112, v210, v112
	v_cndmask_b32_e64 v211, v211, 1.0, s[28:29]
	v_mul_f32_e32 v70, v70, v112
	v_and_b32_e32 v112, 0xffff0000, v209
	v_mul_f32_e32 v112, v211, v112
	v_mul_f32_e32 v71, v71, v112
	s_waitcnt vmcnt(10)
	v_lshlrev_b32_e32 v142, 16, v212
	v_lshlrev_b32_e32 v112, 16, v214
	v_max_f32_e32 v112, v112, v112
	v_max_f32_e32 v112, 0x219392ef, v112
	v_and_b32_e32 v137, 0xffff0000, v214
	v_rcp_f32_e32 v112, v112
	v_max_f32_e32 v137, v137, v137
	v_max_f32_e32 v137, 0x219392ef, v137
	v_lshlrev_b32_e32 v214, 16, v215
	v_rcp_f32_e32 v137, v137
	v_max_f32_e32 v214, v214, v214
	v_max_f32_e32 v214, 0x219392ef, v214
	v_and_b32_e32 v215, 0xffff0000, v215
	v_cndmask_b32_e64 v112, v112, 1.0, s[28:29]
	v_rcp_f32_e32 v214, v214
	v_max_f32_e32 v215, v215, v215
	v_max_f32_e32 v215, 0x219392ef, v215
	v_mul_f32_e32 v112, v112, v142
	v_cndmask_b32_e64 v137, v137, 1.0, s[28:29]
	v_rcp_f32_e32 v215, v215
	v_mul_f32_e32 v60, v60, v112
	v_and_b32_e32 v112, 0xffff0000, v212
	v_mul_f32_e32 v112, v137, v112
	v_cndmask_b32_e64 v214, v214, 1.0, s[28:29]
	v_mul_f32_e32 v61, v61, v112
	v_lshlrev_b32_e32 v112, 16, v213
	v_mul_f32_e32 v112, v214, v112
	v_cndmask_b32_e64 v215, v215, 1.0, s[28:29]
	v_mul_f32_e32 v62, v62, v112
	v_and_b32_e32 v112, 0xffff0000, v213
	v_mul_f32_e32 v112, v215, v112
	v_mul_f32_e32 v63, v63, v112
	s_waitcnt vmcnt(8)
; #define SBAR() __builtin_amdgcn_sched_barrier(0)
; DEVINL int opaque_tid() { int t = threadIdx.x; asm volatile("" : "+v"(t)); return t; }
; DEVINL void phase_merge(const Params& p, int l, char* shm) {
;     ...
;     for (int br = 0; br < 3; ++br) {
;       gemm8_tile<3072, 1024, false>(BR + br * 1024, WB + br * 1024, brow, bcol, acc, shm);
;       const int tid = opaque_tid(), wid = tid >> 6, lane = tid & 63, wr = wid >> 2, wc = wid & 3, fr = lane & 15, fq = lane >> 4;
;       const int hoff = br < 2 ? 2048 : 0; const bool notlast = br < 2;
; #pragma unroll
;       for (int ai = 0; ai < 2; ++ai)
; #pragma unroll
;         for (int m = 0; m < 4; ++m) {
;           const u16* grow = MGT + (size_t)(brow + ai * 128 + wr * 64 + m * 16 + fr) * 6144 + br * 2048 + bcol + wc * 32 + fq * 4;
; #pragma unroll
;           for (int bj = 0; bj < 2; ++bj)
; #pragma unroll
;             for (int n = 0; n < 2; ++n) {
;               const u32x2 g = *reinterpret_cast<const u32x2*>(grow + bj * 128 + n * 16);
;               const u32x2 h = *reinterpret_cast<const u32x2*>(grow + hoff + bj * 128 + n * 16);
;               const float r0 = notlast ? __builtin_amdgcn_rcpf(fmaxf(__uint_as_float(h[0] << 16), 1e-18f)) : 1.f;
;               const float r1 = notlast ? __builtin_amdgcn_rcpf(fmaxf(__uint_as_float(h[0] & 0xffff0000u), 1e-18f)) : 1.f;
;               const float r2 = notlast ? __builtin_amdgcn_rcpf(fmaxf(__uint_as_float(h[1] << 16), 1e-18f)) : 1.f;
;               const float r3 = notlast ? __builtin_amdgcn_rcpf(fmaxf(__uint_as_float(h[1] & 0xffff0000u), 1e-18f)) : 1.f;
;               acc[ai][bj][m][n][0] *= __uint_as_float(g[0] << 16) * r0; acc[ai][bj][m][n][1] *= __uint_as_float(g[0] & 0xffff0000u) * r1;
;               acc[ai][bj][m][n][2] *= __uint_as_float(g[1] << 16) * r2; acc[ai][bj][m][n][3] *= __uint_as_float(g[1] & 0xffff0000u) * r3;
;             }
;           SBAR();
;         }
	v_lshlrev_b32_e32 v142, 16, v216
	v_lshlrev_b32_e32 v112, 16, v218
	v_max_f32_e32 v112, v112, v112
	v_max_f32_e32 v112, 0x219392ef, v112
	v_and_b32_e32 v137, 0xffff0000, v218
	v_rcp_f32_e32 v112, v112
	v_max_f32_e32 v137, v137, v137
	v_max_f32_e32 v137, 0x219392ef, v137
	v_lshlrev_b32_e32 v218, 16, v219
	v_rcp_f32_e32 v137, v137
	v_max_f32_e32 v218, v218, v218
	v_max_f32_e32 v218, 0x219392ef, v218
	v_and_b32_e32 v219, 0xffff0000, v219
	v_cndmask_b32_e64 v112, v112, 1.0, s[28:29]
	v_rcp_f32_e32 v218, v218
	v_max_f32_e32 v219, v219, v219
	v_max_f32_e32 v219, 0x219392ef, v219
	v_mul_f32_e32 v112, v112, v142
	v_cndmask_b32_e64 v137, v137, 1.0, s[28:29]
	v_rcp_f32_e32 v219, v219
	v_mul_f32_e32 v44, v44, v112
	v_and_b32_e32 v112, 0xffff0000, v216
	v_mul_f32_e32 v112, v137, v112
	v_cndmask_b32_e64 v218, v218, 1.0, s[28:29]
	v_mul_f32_e32 v45, v45, v112
	v_lshlrev_b32_e32 v112, 16, v217
	v_mul_f32_e32 v112, v218, v112
	v_cndmask_b32_e64 v219, v219, 1.0, s[28:29]
	v_mul_f32_e32 v46, v46, v112
	v_and_b32_e32 v112, 0xffff0000, v217
	v_mul_f32_e32 v112, v219, v112
	v_mul_f32_e32 v47, v47, v112
	s_waitcnt vmcnt(6)
	v_lshlrev_b32_e32 v142, 16, v220
	v_lshlrev_b32_e32 v112, 16, v222
	v_max_f32_e32 v112, v112, v112
	v_max_f32_e32 v112, 0x219392ef, v112
	v_and_b32_e32 v137, 0xffff0000, v222
	v_rcp_f32_e32 v112, v112
	v_max_f32_e32 v137, v137, v137
	v_max_f32_e32 v137, 0x219392ef, v137
	v_lshlrev_b32_e32 v222, 16, v223
	v_rcp_f32_e32 v137, v137
	v_max_f32_e32 v222, v222, v222
	v_max_f32_e32 v222, 0x219392ef, v222
	v_and_b32_e32 v223, 0xffff0000, v223
	v_cndmask_b32_e64 v112, v112, 1.0, s[28:29]
	v_rcp_f32_e32 v222, v222
	v_max_f32_e32 v223, v223, v223
	v_max_f32_e32 v223, 0x219392ef, v223
	v_mul_f32_e32 v112, v112, v142
	v_cndmask_b32_e64 v137, v137, 1.0, s[28:29]
	v_rcp_f32_e32 v223, v223
	v_mul_f32_e32 v40, v40, v112
	v_and_b32_e32 v112, 0xffff0000, v220
	v_mul_f32_e32 v112, v137, v112
	v_cndmask_b32_e64 v222, v222, 1.0, s[28:29]
	v_mul_f32_e32 v41, v41, v112
	v_lshlrev_b32_e32 v112, 16, v221
	v_mul_f32_e32 v112, v222, v112
	v_cndmask_b32_e64 v223, v223, 1.0, s[28:29]
	v_mul_f32_e32 v42, v42, v112
	v_and_b32_e32 v112, 0xffff0000, v221
	v_mul_f32_e32 v112, v223, v112
	v_mul_f32_e32 v43, v43, v112
	s_waitcnt vmcnt(4)
	v_lshlrev_b32_e32 v142, 16, v224
	v_lshlrev_b32_e32 v112, 16, v226
	v_max_f32_e32 v112, v112, v112
	v_max_f32_e32 v112, 0x219392ef, v112
	v_and_b32_e32 v137, 0xffff0000, v226
	v_rcp_f32_e32 v112, v112
	v_max_f32_e32 v137, v137, v137
	v_max_f32_e32 v137, 0x219392ef, v137
	v_lshlrev_b32_e32 v226, 16, v227
	v_rcp_f32_e32 v137, v137
	v_max_f32_e32 v226, v226, v226
	v_max_f32_e32 v226, 0x219392ef, v226
	v_and_b32_e32 v227, 0xffff0000, v227
	v_cndmask_b32_e64 v112, v112, 1.0, s[28:29]
	v_rcp_f32_e32 v226, v226
	v_max_f32_e32 v227, v227, v227
	v_max_f32_e32 v227, 0x219392ef, v227
	v_mul_f32_e32 v112, v112, v142
	v_cndmask_b32_e64 v137, v137, 1.0, s[28:29]
	v_rcp_f32_e32 v227, v227
	v_mul_f32_e32 v36, v36, v112
	v_and_b32_e32 v112, 0xffff0000, v224
	v_mul_f32_e32 v112, v137, v112
	v_cndmask_b32_e64 v226, v226, 1.0, s[28:29]
	v_mul_f32_e32 v37, v37, v112
	v_lshlrev_b32_e32 v112, 16, v225
	v_mul_f32_e32 v112, v226, v112
	v_cndmask_b32_e64 v227, v227, 1.0, s[28:29]
	v_mul_f32_e32 v38, v38, v112
	v_and_b32_e32 v112, 0xffff0000, v225
	v_mul_f32_e32 v112, v227, v112
	v_mul_f32_e32 v39, v39, v112
	s_waitcnt vmcnt(2)
	v_lshlrev_b32_e32 v142, 16, v228
	v_lshlrev_b32_e32 v112, 16, v230
	v_max_f32_e32 v112, v112, v112
	v_max_f32_e32 v112, 0x219392ef, v112
	v_and_b32_e32 v137, 0xffff0000, v230
	v_rcp_f32_e32 v112, v112
	v_max_f32_e32 v137, v137, v137
	v_max_f32_e32 v137, 0x219392ef, v137
	v_lshlrev_b32_e32 v230, 16, v231
	v_rcp_f32_e32 v137, v137
	v_max_f32_e32 v230, v230, v230
	v_max_f32_e32 v230, 0x219392ef, v230
	v_and_b32_e32 v231, 0xffff0000, v231
	v_cndmask_b32_e64 v112, v112, 1.0, s[28:29]
	v_rcp_f32_e32 v230, v230
	v_max_f32_e32 v231, v231, v231
	v_max_f32_e32 v231, 0x219392ef, v231
	v_mul_f32_e32 v112, v112, v142
	v_cndmask_b32_e64 v137, v137, 1.0, s[28:29]
	v_rcp_f32_e32 v231, v231
	v_mul_f32_e32 v28, v28, v112
	v_and_b32_e32 v112, 0xffff0000, v228
	v_mul_f32_e32 v112, v137, v112
	v_cndmask_b32_e64 v230, v230, 1.0, s[28:29]
	v_mul_f32_e32 v29, v29, v112
	v_lshlrev_b32_e32 v112, 16, v229
	v_mul_f32_e32 v112, v230, v112
	v_cndmask_b32_e64 v231, v231, 1.0, s[28:29]
	v_mul_f32_e32 v30, v30, v112
	v_and_b32_e32 v112, 0xffff0000, v229
	v_mul_f32_e32 v112, v231, v112
	v_mul_f32_e32 v31, v31, v112
	s_waitcnt vmcnt(0)
	v_lshlrev_b32_e32 v142, 16, v232
	v_lshlrev_b32_e32 v112, 16, v234
	v_max_f32_e32 v112, v112, v112
	v_max_f32_e32 v112, 0x219392ef, v112
	v_and_b32_e32 v137, 0xffff0000, v234
	v_rcp_f32_e32 v112, v112
	v_max_f32_e32 v137, v137, v137
	v_max_f32_e32 v137, 0x219392ef, v137
	v_lshlrev_b32_e32 v234, 16, v235
	v_rcp_f32_e32 v137, v137
	v_max_f32_e32 v234, v234, v234
	v_max_f32_e32 v234, 0x219392ef, v234
	v_and_b32_e32 v235, 0xffff0000, v235
	v_cndmask_b32_e64 v112, v112, 1.0, s[28:29]
	v_rcp_f32_e32 v234, v234
	v_max_f32_e32 v235, v235, v235
	v_max_f32_e32 v235, 0x219392ef, v235
	v_mul_f32_e32 v112, v112, v142
	v_cndmask_b32_e64 v137, v137, 1.0, s[28:29]
	v_rcp_f32_e32 v235, v235
	v_mul_f32_e32 v12, v12, v112
	v_and_b32_e32 v112, 0xffff0000, v232
	v_mul_f32_e32 v112, v137, v112
	v_cndmask_b32_e64 v234, v234, 1.0, s[28:29]
	v_mul_f32_e32 v13, v13, v112
	v_lshlrev_b32_e32 v112, 16, v233
	v_mul_f32_e32 v112, v234, v112
	v_cndmask_b32_e64 v235, v235, 1.0, s[28:29]
	v_mul_f32_e32 v14, v14, v112
	v_and_b32_e32 v112, 0xffff0000, v233
	v_mul_f32_e32 v112, v235, v112
	v_mul_f32_e32 v15, v15, v112
	s_add_i32 s27, s27, 1
	s_add_u32 s20, s20, 0x800
	s_addc_u32 s21, s21, 0
	s_cmp_eq_u32 s27, 3
	s_cbranch_scc1 .LBB0_665
